# RG-LRU scan: independent LDS reads of intervals 2 and 4 hoisted ahead of the FMA chains (register renaming into v242-v255), both unrolled tiles; on top of v50
# baseline (speedup 1.0000x reference)
; __device__ __forceinline__ float bf2f(bf16_t v) { return __uint_as_float(((unsigned)v) << 16); }
; __device__ __forceinline__ float sigmoidf_(float x) { return __builtin_amdgcn_rcpf(1.f + __expf(-x)); }
; #define MFMA16(a, b, c) __builtin_amdgcn_mfma_f32_16x16x32_bf16((a), (b), (c), 0, 0, 0)
; __device__ __forceinline__ void rglru_unit(const Params& p, const WS& ws, int j, int u, bool dry = false) {
;     ...
; #pragma unroll
;       for (int ks = 0; ks < 4; ++ks) {
;         const bf16x8 xf = *(const bf16x8*)(XC + (16 * w + lr) * 136 + 32 * ks + 8 * lq);
; #pragma unroll
;         for (int gate = 0; gate < 2; ++gate)
; #pragma unroll
;           for (int mt = 0; mt < 2; ++mt) {
;             const bf16x8 wf = *(const bf16x8*)(WG + (gate * 32 + 16 * mt + lr) * 136 + 32 * ks + 8 * lq);
;             ga_[gate][mt] = MFMA16(wf, xf, ga_[gate][mt]);
;           }
;       }
;       const int tok = 16 * w + lr;
; #pragma unroll
;       for (int mt = 0; mt < 2; ++mt)
; #pragma unroll
;         for (int jj = 0; jj < 4; ++jj) {
;           const int n = 16 * mt + 4 * lq + jj;
;           const float xcv = bf2f(XC[tok * 136 + 32 * jq + n]);
;           const float r = sigmoidf_(ga_[0][mt][jj] + ba[mt][jj]);
;           const float ig = sigmoidf_(ga_[1][mt][jj] + bx[mt][jj]);
;           const float la = -r * sp[mt][jj];
;           const float a = __expf(la);
;           const float x2 = 2.f * la;
;           const float om = x2 > -0.02f ? -x2 * (1.f + 0.5f * x2 * (1.f + x2 * (1.f / 3.f))) : 1.f - a * a;
;           const float mult = __builtin_amdgcn_sqrtf(fmaxf(om, 0.f));
;           AUa[tok * 33 + n] = a;
;           AUu[tok * 33 + n] = mult * ig * xcv;
;         }
.LBB0_1420:
	ds_read_b128 v[52:55], v111
	ds_read_b128 v[56:59], v112 offset:17408
	ds_read_b128 v[60:63], v112 offset:21760
	ds_read_b128 v[64:67], v112 offset:26112
	ds_read_b128 v[136:139], v112 offset:30464
	s_waitcnt lgkmcnt(3)
	v_mfma_f32_16x16x32_bf16 v[56:59], v[56:59], v[52:55], 0
	s_waitcnt lgkmcnt(2)
	v_mfma_f32_16x16x32_bf16 v[60:63], v[60:63], v[52:55], 0
	s_waitcnt lgkmcnt(1)
	v_mfma_f32_16x16x32_bf16 v[64:67], v[64:67], v[52:55], 0
	s_waitcnt lgkmcnt(0)
	v_mfma_f32_16x16x32_bf16 v[52:55], v[136:139], v[52:55], 0
	ds_read_b128 v[136:139], v111 offset:64
	ds_read_b128 v[140:143], v112 offset:17472
	s_waitcnt lgkmcnt(0)
	v_mfma_f32_16x16x32_bf16 v[56:59], v[140:143], v[136:139], v[56:59]
	ds_read_b128 v[140:143], v112 offset:21824
	s_waitcnt lgkmcnt(0)
	v_mfma_f32_16x16x32_bf16 v[60:63], v[140:143], v[136:139], v[60:63]
	ds_read_b128 v[140:143], v112 offset:26176
	s_waitcnt lgkmcnt(0)
	v_mfma_f32_16x16x32_bf16 v[64:67], v[140:143], v[136:139], v[64:67]
	ds_read_b128 v[140:143], v112 offset:30528
	s_waitcnt lgkmcnt(0)
	v_mfma_f32_16x16x32_bf16 v[52:55], v[140:143], v[136:139], v[52:55]
	ds_read_b128 v[136:139], v111 offset:128
	ds_read_b128 v[140:143], v112 offset:17536
	s_waitcnt lgkmcnt(0)
	v_mfma_f32_16x16x32_bf16 v[56:59], v[140:143], v[136:139], v[56:59]
	ds_read_b128 v[140:143], v112 offset:21888
	s_waitcnt lgkmcnt(0)
	v_mfma_f32_16x16x32_bf16 v[60:63], v[140:143], v[136:139], v[60:63]
	ds_read_b128 v[140:143], v112 offset:26240
	s_waitcnt lgkmcnt(0)
	v_mfma_f32_16x16x32_bf16 v[140:143], v[140:143], v[136:139], v[64:67]
	s_nop 2
	ds_read_b128 v[64:67], v112 offset:30592
	s_waitcnt lgkmcnt(0)
	v_mfma_f32_16x16x32_bf16 v[52:55], v[64:67], v[136:139], v[52:55]
	ds_read_b128 v[136:139], v111 offset:192
	ds_read_b128 v[64:67], v112 offset:17600
	ds_read_u16 v13, v113
	s_waitcnt lgkmcnt(1)
	v_mfma_f32_16x16x32_bf16 v[64:67], v[64:67], v[136:139], v[56:59]
	s_nop 2
	ds_read_b128 v[56:59], v112 offset:21952
	s_waitcnt lgkmcnt(0)
	v_mfma_f32_16x16x32_bf16 v[56:59], v[56:59], v[136:139], v[60:63]
	s_nop 2
	ds_read_b128 v[60:63], v112 offset:26304
	v_add_f32_e32 v14, v0, v64
	v_mul_f32_e32 v14, 0xbfb8aa3b, v14
	v_exp_f32_e32 v14, v14
	s_waitcnt lgkmcnt(0)
	v_mfma_f32_16x16x32_bf16 v[60:63], v[60:63], v[136:139], v[140:143]
	s_nop 2
	ds_read_b128 v[140:143], v112 offset:30656
	v_add_f32_e32 v14, 1.0, v14
	v_rcp_f32_e64 v14, -v14
	s_waitcnt lgkmcnt(0)
	v_mfma_f32_16x16x32_bf16 v[52:55], v[140:143], v[136:139], v[52:55]
	v_mul_f32_e32 v14, v89, v14
	v_mul_f32_e32 v15, 0x3fb8aa3b, v14
	v_exp_f32_e32 v15, v15
	v_add_f32_e32 v14, v14, v14
	v_cmp_nlt_f32_e64 s[52:53], s29, v14
	s_and_saveexec_b64 s[4:5], s[52:53]
	s_xor_b64 s[4:5], exec, s[4:5]
	v_fma_f32 v64, -v15, v15, 1.0
	s_andn2_saveexec_b64 s[4:5], s[4:5]
	v_pk_mul_f32 v[136:137], v[14:15], s[88:89] op_sel_hi:[0,1]
	v_add_f32_e32 v64, 1.0, v137
	v_fma_f32 v64, v136, v64, 1.0
	v_mul_f32_e64 v64, v64, -v14
	s_or_b64 exec, exec, s[4:5]
	v_add_f32_e32 v14, v8, v60
	v_max_f32_e32 v60, v64, v64
	v_add_f32_e32 v64, v1, v65
	v_mul_f32_e32 v14, 0xbfb8aa3b, v14
	v_mul_f32_e32 v64, 0xbfb8aa3b, v64
	v_exp_f32_e32 v14, v14
	v_exp_f32_e32 v64, v64
	v_max_f32_e32 v60, 0, v60
	v_sqrt_f32_e32 v60, v60
	v_add_f32_e32 v14, 1.0, v14
	v_add_f32_e32 v64, 1.0, v64
	v_rcp_f32_e32 v14, v14
	v_rcp_f32_e64 v64, -v64
	v_lshlrev_b32_e32 v13, 16, v13
	v_mul_f32_e32 v14, v14, v60
	v_mul_f32_e32 v64, v93, v64
	v_mul_f32_e32 v14, v14, v13
	ds_read_u16 v60, v113 offset:2
	v_mul_f32_e32 v13, 0x3fb8aa3b, v64
	v_exp_f32_e32 v13, v13
	ds_write2st64_b32 v72, v15, v14 offset0:136 offset1:169
	v_add_f32_e32 v14, v64, v64
	v_cmp_nlt_f32_e64 s[52:53], s29, v14
	s_and_saveexec_b64 s[4:5], s[52:53]
	s_xor_b64 s[4:5], exec, s[4:5]
	v_fma_f32 v15, -v13, v13, 1.0
	s_andn2_saveexec_b64 s[4:5], s[4:5]
	v_pk_mul_f32 v[64:65], v[14:15], s[88:89] op_sel_hi:[0,1]
	v_add_f32_e32 v15, 1.0, v65
	v_fma_f32 v15, v64, v15, 1.0
	v_mul_f32_e64 v15, v15, -v14
	s_or_b64 exec, exec, s[4:5]
	s_waitcnt lgkmcnt(1)
	v_lshlrev_b32_e32 v14, 16, v60
	v_add_f32_e32 v60, v9, v61
	v_mul_f32_e32 v60, 0xbfb8aa3b, v60
	v_exp_f32_e32 v60, v60
	v_max_f32_e32 v15, v15, v15
	v_max_f32_e32 v15, 0, v15
	v_sqrt_f32_e32 v15, v15
	v_add_f32_e32 v60, 1.0, v60
	v_rcp_f32_e32 v60, v60
	v_add_u32_e32 v135, 4, v72
	v_mul_f32_e32 v15, v60, v15
	v_mul_f32_e32 v14, v15, v14
	ds_write2st64_b32 v135, v13, v14 offset0:136 offset1:169
	v_add_f32_e32 v14, v2, v66
	v_mul_f32_e32 v14, 0xbfb8aa3b, v14
	v_exp_f32_e32 v14, v14
	ds_read_u16 v13, v113 offset:4
	v_add_f32_e32 v14, 1.0, v14
	v_rcp_f32_e64 v14, -v14
	s_nop 0
	v_mul_f32_e32 v14, v95, v14
	v_mul_f32_e32 v15, 0x3fb8aa3b, v14
	v_exp_f32_e32 v15, v15
	v_add_f32_e32 v14, v14, v14
	v_cmp_nlt_f32_e64 s[52:53], s29, v14
	s_and_saveexec_b64 s[4:5], s[52:53]
	s_xor_b64 s[4:5], exec, s[4:5]
	v_fma_f32 v60, -v15, v15, 1.0
	s_andn2_saveexec_b64 s[4:5], s[4:5]
	v_pk_mul_f32 v[60:61], v[14:15], s[88:89] op_sel_hi:[0,1]
	v_add_f32_e32 v61, 1.0, v61
	v_fma_f32 v60, v60, v61, 1.0
	v_mul_f32_e64 v60, v60, -v14
	s_or_b64 exec, exec, s[4:5]
	v_add_f32_e32 v14, v10, v62
	v_mul_f32_e32 v14, 0xbfb8aa3b, v14
	v_exp_f32_e32 v14, v14
	v_max_f32_e32 v60, v60, v60
	v_max_f32_e32 v60, 0, v60
	v_sqrt_f32_e32 v60, v60
	v_add_f32_e32 v14, 1.0, v14
	v_rcp_f32_e32 v14, v14
	s_waitcnt lgkmcnt(0)
; __device__ __forceinline__ float bf2f(bf16_t v) { return __uint_as_float(((unsigned)v) << 16); }
; __device__ __forceinline__ float sigmoidf_(float x) { return __builtin_amdgcn_rcpf(1.f + __expf(-x)); }
; __device__ __forceinline__ void rglru_unit(const Params& p, const WS& ws, int j, int u, bool dry = false) {
;     ...
; #pragma unroll
;       for (int mt = 0; mt < 2; ++mt)
; #pragma unroll
;         for (int jj = 0; jj < 4; ++jj) {
;           const int n = 16 * mt + 4 * lq + jj;
;           const float xcv = bf2f(XC[tok * 136 + 32 * jq + n]);
;           const float r = sigmoidf_(ga_[0][mt][jj] + ba[mt][jj]);
;           const float ig = sigmoidf_(ga_[1][mt][jj] + bx[mt][jj]);
;           const float la = -r * sp[mt][jj];
;           const float a = __expf(la);
;           const float x2 = 2.f * la;
;           const float om = x2 > -0.02f ? -x2 * (1.f + 0.5f * x2 * (1.f + x2 * (1.f / 3.f))) : 1.f - a * a;
;           const float mult = __builtin_amdgcn_sqrtf(fmaxf(om, 0.f));
;           AUa[tok * 33 + n] = a;
;           AUu[tok * 33 + n] = mult * ig * xcv;
;         }
;     }
;     __syncthreads();
	v_lshlrev_b32_e32 v13, 16, v13
	v_add_u32_e32 v136, 8, v72
	v_mul_f32_e32 v14, v14, v60
	v_mul_f32_e32 v13, v14, v13
	v_add_f32_e32 v14, v3, v67
	v_mul_f32_e32 v14, 0xbfb8aa3b, v14
	v_exp_f32_e32 v14, v14
	ds_write2st64_b32 v136, v15, v13 offset0:136 offset1:169
	ds_read_u16 v13, v113 offset:6
	v_add_f32_e32 v14, 1.0, v14
	v_rcp_f32_e64 v14, -v14
	s_nop 0
	v_mul_f32_e32 v14, v96, v14
	v_mul_f32_e32 v15, 0x3fb8aa3b, v14
	v_exp_f32_e32 v15, v15
	v_add_f32_e32 v14, v14, v14
	v_cmp_nlt_f32_e64 s[52:53], s29, v14
	s_and_saveexec_b64 s[4:5], s[52:53]
	s_xor_b64 s[4:5], exec, s[4:5]
	v_fma_f32 v60, -v15, v15, 1.0
	s_andn2_saveexec_b64 s[4:5], s[4:5]
	v_pk_mul_f32 v[60:61], v[14:15], s[88:89] op_sel_hi:[0,1]
	v_add_f32_e32 v61, 1.0, v61
	v_fma_f32 v60, v60, v61, 1.0
	v_mul_f32_e64 v60, v60, -v14
	s_or_b64 exec, exec, s[4:5]
	v_add_f32_e32 v14, v11, v63
	v_mul_f32_e32 v14, 0xbfb8aa3b, v14
	v_exp_f32_e32 v14, v14
	v_max_f32_e32 v60, v60, v60
	v_max_f32_e32 v60, 0, v60
	v_sqrt_f32_e32 v60, v60
	v_add_f32_e32 v14, 1.0, v14
	v_rcp_f32_e32 v14, v14
	s_waitcnt lgkmcnt(0)
	v_lshlrev_b32_e32 v13, 16, v13
	v_add_u32_e32 v139, 12, v72
	v_mul_f32_e32 v14, v14, v60
	v_mul_f32_e32 v13, v14, v13
	v_add_f32_e32 v14, v4, v56
	v_mul_f32_e32 v14, 0xbfb8aa3b, v14
	v_exp_f32_e32 v14, v14
	ds_write2st64_b32 v139, v15, v13 offset0:136 offset1:169
	ds_read_u16 v13, v113 offset:32
	v_add_f32_e32 v14, 1.0, v14
	v_rcp_f32_e64 v14, -v14
	s_nop 0
	v_mul_f32_e32 v14, v97, v14
	v_mul_f32_e32 v15, 0x3fb8aa3b, v14
	v_exp_f32_e32 v15, v15
	v_add_f32_e32 v14, v14, v14
	v_cmp_nlt_f32_e64 s[52:53], s29, v14
	s_and_saveexec_b64 s[4:5], s[52:53]
	s_xor_b64 s[4:5], exec, s[4:5]
	v_fma_f32 v56, -v15, v15, 1.0
	s_andn2_saveexec_b64 s[4:5], s[4:5]
	v_pk_mul_f32 v[60:61], v[14:15], s[88:89] op_sel_hi:[0,1]
	v_add_f32_e32 v56, 1.0, v61
	v_fma_f32 v56, v60, v56, 1.0
	v_mul_f32_e64 v56, v56, -v14
	s_or_b64 exec, exec, s[4:5]
	v_add_f32_e32 v14, v16, v52
	v_mul_f32_e32 v14, 0xbfb8aa3b, v14
	v_exp_f32_e32 v14, v14
	v_max_f32_e32 v52, v56, v56
	v_max_f32_e32 v52, 0, v52
	v_sqrt_f32_e32 v52, v52
	v_add_f32_e32 v14, 1.0, v14
	v_rcp_f32_e32 v14, v14
	s_waitcnt lgkmcnt(0)
	v_lshlrev_b32_e32 v13, 16, v13
	v_add_u32_e32 v141, 64, v72
	v_mul_f32_e32 v14, v14, v52
	v_mul_f32_e32 v13, v14, v13
	v_add_f32_e32 v14, v5, v57
	v_mul_f32_e32 v14, 0xbfb8aa3b, v14
	v_exp_f32_e32 v14, v14
	ds_write2st64_b32 v141, v15, v13 offset0:136 offset1:169
	ds_read_u16 v13, v113 offset:34
	v_add_f32_e32 v14, 1.0, v14
	v_rcp_f32_e64 v14, -v14
	s_nop 0
	v_mul_f32_e32 v14, v98, v14
	v_mul_f32_e32 v15, 0x3fb8aa3b, v14
	v_exp_f32_e32 v15, v15
	v_add_f32_e32 v14, v14, v14
	v_cmp_nlt_f32_e64 s[52:53], s29, v14
	s_and_saveexec_b64 s[4:5], s[52:53]
	s_xor_b64 s[4:5], exec, s[4:5]
	v_fma_f32 v52, -v15, v15, 1.0
	s_andn2_saveexec_b64 s[4:5], s[4:5]
	v_pk_mul_f32 v[56:57], v[14:15], s[88:89] op_sel_hi:[0,1]
	v_add_f32_e32 v52, 1.0, v57
	v_fma_f32 v52, v56, v52, 1.0
	v_mul_f32_e64 v52, v52, -v14
	s_or_b64 exec, exec, s[4:5]
	v_add_f32_e32 v14, v17, v53
	v_mul_f32_e32 v14, 0xbfb8aa3b, v14
	v_exp_f32_e32 v14, v14
	v_max_f32_e32 v52, v52, v52
	v_max_f32_e32 v52, 0, v52
	v_sqrt_f32_e32 v52, v52
	v_add_f32_e32 v14, 1.0, v14
	v_rcp_f32_e32 v14, v14
	s_waitcnt lgkmcnt(0)
	v_lshlrev_b32_e32 v13, 16, v13
	v_add_u32_e32 v142, 0x44, v72
	v_mul_f32_e32 v14, v14, v52
	v_mul_f32_e32 v13, v14, v13
	v_add_f32_e32 v14, v6, v58
	v_mul_f32_e32 v14, 0xbfb8aa3b, v14
	v_exp_f32_e32 v14, v14
	ds_write2st64_b32 v142, v15, v13 offset0:136 offset1:169
	ds_read_u16 v13, v113 offset:36
	v_add_f32_e32 v14, 1.0, v14
	v_rcp_f32_e64 v14, -v14
	s_nop 0
	v_mul_f32_e32 v14, v99, v14
	v_mul_f32_e32 v15, 0x3fb8aa3b, v14
	v_exp_f32_e32 v15, v15
	v_add_f32_e32 v14, v14, v14
	v_cmp_nlt_f32_e64 s[52:53], s29, v14
	s_and_saveexec_b64 s[4:5], s[52:53]
	s_xor_b64 s[4:5], exec, s[4:5]
	v_fma_f32 v52, -v15, v15, 1.0
	s_andn2_saveexec_b64 s[4:5], s[4:5]
	v_pk_mul_f32 v[52:53], v[14:15], s[88:89] op_sel_hi:[0,1]
	v_add_f32_e32 v53, 1.0, v53
	v_fma_f32 v52, v52, v53, 1.0
	v_mul_f32_e64 v52, v52, -v14
	s_or_b64 exec, exec, s[4:5]
	v_add_f32_e32 v14, v18, v54
	v_mul_f32_e32 v14, 0xbfb8aa3b, v14
	v_exp_f32_e32 v14, v14
	v_max_f32_e32 v52, v52, v52
	v_max_f32_e32 v52, 0, v52
	v_sqrt_f32_e32 v52, v52
	v_add_f32_e32 v14, 1.0, v14
	v_rcp_f32_e32 v14, v14
	s_waitcnt lgkmcnt(0)
	v_lshlrev_b32_e32 v13, 16, v13
	v_add_u32_e32 v144, 0x48, v72
	v_mul_f32_e32 v14, v14, v52
	v_mul_f32_e32 v13, v14, v13
	v_add_f32_e32 v14, v7, v59
	v_mul_f32_e32 v14, 0xbfb8aa3b, v14
	v_exp_f32_e32 v14, v14
	ds_write2st64_b32 v144, v15, v13 offset0:136 offset1:169
	ds_read_u16 v13, v113 offset:38
	v_add_f32_e32 v14, 1.0, v14
	v_rcp_f32_e64 v14, -v14
	s_nop 0
	v_mul_f32_e32 v14, v105, v14
	v_mul_f32_e32 v15, 0x3fb8aa3b, v14
	v_exp_f32_e32 v15, v15
	v_add_f32_e32 v14, v14, v14
	v_cmp_nlt_f32_e64 s[52:53], s29, v14
	s_and_saveexec_b64 s[4:5], s[52:53]
	s_xor_b64 s[4:5], exec, s[4:5]
	v_fma_f32 v52, -v15, v15, 1.0
	s_andn2_saveexec_b64 s[4:5], s[4:5]
	v_pk_mul_f32 v[52:53], v[14:15], s[88:89] op_sel_hi:[0,1]
	v_add_f32_e32 v53, 1.0, v53
	v_fma_f32 v52, v52, v53, 1.0
	v_mul_f32_e64 v52, v52, -v14
	s_or_b64 exec, exec, s[4:5]
	v_add_f32_e32 v14, v19, v55
	v_mul_f32_e32 v14, 0xbfb8aa3b, v14
	v_exp_f32_e32 v14, v14
	v_max_f32_e32 v52, v52, v52
	v_max_f32_e32 v52, 0, v52
	v_sqrt_f32_e32 v52, v52
	v_add_f32_e32 v14, 1.0, v14
	v_rcp_f32_e32 v14, v14
	s_waitcnt lgkmcnt(0)
	v_lshlrev_b32_e32 v13, 16, v13
	v_add_u32_e32 v145, 0x4c, v72
	v_add_u32_e32 v137, 0x8800, v114
	v_mul_f32_e32 v14, v14, v52
	v_mul_f32_e32 v13, v14, v13
	v_add_u32_e32 v138, 0xa800, v114
	ds_write2st64_b32 v145, v15, v13 offset0:136 offset1:169
	s_waitcnt lgkmcnt(0)
	s_barrier
; __device__ __forceinline__ void rglru_unit(const Params& p, const WS& ws, int j, int u, bool dry = false) {
;     ...
;     {
;       float A = 1.f, Hh = 0.f;
; #pragma unroll
;       for (int i = 0; i < 8; ++i) {
;         const float a = AUa[(8 * ssg + i) * 33 + sc], uu = AUu[(8 * ssg + i) * 33 + sc];
;         Hh = a * Hh + uu; A *= a;
;       }
;       SEGA[ssg * 32 + sc] = A; SEGH[ssg * 32 + sc] = Hh;
;     }
;     __syncthreads();
;     float hin = CARRY[sc];
; #pragma unroll
;     for (int s2 = 0; s2 < 7; ++s2)
;       if (s2 < ssg) hin = SEGA[s2 * 32 + sc] * hin + SEGH[s2 * 32 + sc];
	v_add_u32_e32 v140, 0xac00, v114
	ds_read2_b32 v[242:243], v137 offset1:33
	ds_read2_b32 v[244:245], v138 offset0:64 offset1:97
	ds_read2_b32 v[246:247], v137 offset0:66 offset1:99
	ds_read2_b32 v[248:249], v138 offset0:130 offset1:163
	ds_read2_b32 v[250:251], v137 offset0:132 offset1:165
	ds_read2_b32 v[252:253], v138 offset0:196 offset1:229
	ds_read2_b32 v[14:15], v137 offset0:198 offset1:231
	ds_read2_b32 v[54:55], v140 offset0:6 offset1:39
	s_waitcnt lgkmcnt(6)
	v_fma_f32 v255, 0, v242, v244
	v_fmac_f32_e32 v245, v255, v243
	v_mul_f32_e32 v13, v242, v243
	s_waitcnt lgkmcnt(5)
	v_mul_f32_e32 v13, v13, v246
	s_waitcnt lgkmcnt(4)
	v_fma_f32 v254, v245, v246, v248
	v_fmac_f32_e32 v249, v254, v247
	v_mul_f32_e32 v13, v13, v247
	s_waitcnt lgkmcnt(3)
	v_mul_f32_e32 v13, v13, v250
	s_waitcnt lgkmcnt(2)
	v_fma_f32 v252, v249, v250, v252
	v_fmac_f32_e32 v253, v252, v251
	v_mul_f32_e32 v13, v13, v251
	s_waitcnt lgkmcnt(1)
	v_mul_f32_e32 v13, v13, v14
	s_waitcnt lgkmcnt(0)
	v_fma_f32 v52, v253, v14, v54
	v_fmac_f32_e32 v55, v52, v15
	v_mul_f32_e32 v13, v13, v15
	ds_write2st64_b32 v78, v13, v55 offset0:202 offset1:206
	s_waitcnt lgkmcnt(0)
	s_barrier
	ds_read_b32 v13, v115 offset:53760
	s_and_saveexec_b64 s[4:5], vcc
	s_cbranch_execz .LBB0_1548
	ds_read2st64_b32 v[14:15], v115 offset0:202 offset1:206
	s_waitcnt lgkmcnt(0)
	v_fmac_f32_e32 v15, v13, v14
	v_mov_b32_e32 v13, v15
	s_or_b64 exec, exec, s[4:5]
	v_add_u32_e32 v143, 0x80, v115
	s_and_saveexec_b64 s[4:5], s[38:39]
	s_cbranch_execnz .LBB0_1549

; __device__ __forceinline__ float bf2f(bf16_t v) { return __uint_as_float(((unsigned)v) << 16); }
; __device__ __forceinline__ bf16_t f2bf(float f) { return (bf16_t)(cvt_pk_bf16(f, 0.f) & 0xffffu); }
; __device__ __forceinline__ float siluf_(float x) { return x * __builtin_amdgcn_rcpf(1.f + __expf(-x)); }
; __device__ __forceinline__ void rglru_unit(const Params& p, const WS& ws, int j, int u, bool dry = false) {
;     ...
;   auto body = [&](int tile, u32x4 (&xin)[4], bf16_t (&gav)[8]) {
;     const int t0 = 64 * tile;
; #pragma unroll
;     for (int i = 0; i < 4; ++i) {
;       const int ci = tid + 256 * i; const int row = ci >> 4, ch = ci & 15;
;       *(u32x4*)(XC + row * 136 + 8 * ch) = xin[i];
;     }
;     float gcur[8];
; #pragma unroll
;     for (int i = 0; i < 8; ++i) gcur[i] = bf2f(gav[i]);
;     __syncthreads();
;     flush_y();
;     ...
;     {
;       float h = hin;
; #pragma unroll
;       for (int i = 0; i < 8; ++i) {
;         const float a = AUa[(8 * ssg + i) * 33 + sc], uu = AUu[(8 * ssg + i) * 33 + sc];
;         h = a * h + uu;
;         const int t = t0 + 8 * ssg + i;
;         ypend[i] = f2bf(h * siluf_(gcur[i]));
;       }
;       if (ssg == 7) CARRY[sc] = h;
;       ypend_t0 = t0;
.LBB0_1460:
	s_or_b64 exec, exec, s[4:5]
	s_waitcnt lgkmcnt(0)
	s_barrier
	ds_read2_b32 v[242:243], v137 offset1:33
	ds_read2_b32 v[56:57], v138 offset0:64 offset1:97
	ds_read2_b32 v[244:245], v137 offset0:66 offset1:99
	ds_read2_b32 v[54:55], v138 offset0:130 offset1:163
	ds_read2_b32 v[246:247], v137 offset0:132 offset1:165
	ds_read2_b32 v[52:53], v138 offset0:196 offset1:229
	ds_read2_b32 v[58:59], v137 offset0:198 offset1:231
	ds_read2_b32 v[14:15], v140 offset0:6 offset1:39
	s_waitcnt lgkmcnt(6)
	v_fma_f32 v56, v13, v242, v56
	v_fmac_f32_e32 v57, v56, v243
	s_waitcnt lgkmcnt(4)
	v_fma_f32 v54, v57, v244, v54
	v_fmac_f32_e32 v55, v54, v245
	s_waitcnt lgkmcnt(2)
	v_fma_f32 v52, v55, v246, v52
	v_fmac_f32_e32 v53, v52, v247
	s_waitcnt lgkmcnt(0)
	v_fma_f32 v13, v53, v58, v14
	v_fmac_f32_e32 v15, v13, v59
	s_and_saveexec_b64 s[4:5], s[50:51]
	ds_write_b32 v115, v15 offset:53760
	s_or_b64 exec, exec, s[4:5]
	v_lshlrev_b32_e32 v14, 16, v120
	v_mul_f32_e32 v58, 0xbfb8aa3b, v14
	v_exp_f32_e32 v58, v58
	v_lshlrev_b32_e32 v59, 16, v119
	v_lshlrev_b32_e32 v60, 16, v122
	v_lshlrev_b32_e32 v61, 16, v121
	v_add_f32_e32 v58, 1.0, v58
	v_rcp_f32_e32 v58, v58
	v_lshlrev_b32_e32 v62, 16, v124
	v_lshlrev_b32_e32 v63, 16, v123
	v_lshlrev_b32_e32 v64, 16, v128
	v_mul_f32_e32 v14, v58, v14
	v_mul_f32_e32 v14, v14, v56
	v_cvt_pk_bf16_f32 v58, v14, s0
	v_mul_f32_e32 v14, 0xbfb8aa3b, v59
	v_exp_f32_e32 v14, v14
	v_lshlrev_b32_e32 v65, 16, v127
	s_cmp_gt_u32 s7, 32
	v_add_f32_e32 v14, 1.0, v14
	v_rcp_f32_e32 v14, v14
	s_nop 0
	v_mul_f32_e32 v14, v14, v59
	v_mul_f32_e32 v14, v14, v57
	v_cvt_pk_bf16_f32 v59, v14, s0
	v_mul_f32_e32 v14, 0xbfb8aa3b, v60
	v_exp_f32_e32 v14, v14
	s_nop 0
	v_add_f32_e32 v14, 1.0, v14
	v_rcp_f32_e32 v14, v14
	s_nop 0
	v_mul_f32_e32 v14, v14, v60
	v_mul_f32_e32 v14, v14, v54
	v_cvt_pk_bf16_f32 v56, v14, s0
	v_mul_f32_e32 v14, 0xbfb8aa3b, v61
	v_exp_f32_e32 v14, v14
	s_nop 0
	v_add_f32_e32 v14, 1.0, v14
	v_rcp_f32_e32 v14, v14
	s_nop 0
	v_mul_f32_e32 v14, v14, v61
	v_mul_f32_e32 v14, v14, v55
	v_cvt_pk_bf16_f32 v57, v14, s0
	v_mul_f32_e32 v14, 0xbfb8aa3b, v62
	v_exp_f32_e32 v14, v14
	s_nop 0
	v_add_f32_e32 v14, 1.0, v14
	v_rcp_f32_e32 v14, v14
	s_nop 0
	v_mul_f32_e32 v14, v14, v62
	v_mul_f32_e32 v14, v14, v52
	v_cvt_pk_bf16_f32 v54, v14, s0
	v_mul_f32_e32 v14, 0xbfb8aa3b, v63
	v_exp_f32_e32 v14, v14
	s_nop 0
	v_add_f32_e32 v14, 1.0, v14
	v_rcp_f32_e32 v14, v14
	s_nop 0
	v_mul_f32_e32 v14, v14, v63
	v_mul_f32_e32 v14, v14, v53
	v_cvt_pk_bf16_f32 v55, v14, s0
	v_mul_f32_e32 v14, 0xbfb8aa3b, v64
	v_exp_f32_e32 v14, v14
	s_nop 0
	v_add_f32_e32 v14, 1.0, v14
	v_rcp_f32_e32 v14, v14
	s_nop 0
	v_mul_f32_e32 v14, v14, v64
	v_mul_f32_e32 v13, v14, v13
	v_cvt_pk_bf16_f32 v14, v13, s0
	v_mul_f32_e32 v13, 0xbfb8aa3b, v65
	v_exp_f32_e32 v13, v13
	s_nop 0
	v_add_f32_e32 v13, 1.0, v13
	v_rcp_f32_e32 v13, v13
	s_nop 0
	v_mul_f32_e32 v13, v13, v65
	v_mul_f32_e32 v13, v13, v15
	v_cvt_pk_bf16_f32 v15, v13, s0
	s_cbranch_scc1 .LBB0_1554
	v_add_u32_e32 v60, s6, v83
	v_cmp_gt_i32_e64 s[52:53], s15, v60
	v_add_u32_e32 v52, s6, v69
	ds_write_b128 v106, v[36:39]
	ds_write_b128 v107, v[40:43]
	ds_write_b128 v109, v[44:47]
	ds_write_b128 v110, v[48:51]
	s_waitcnt lgkmcnt(0)
	s_barrier
	s_and_saveexec_b64 s[4:5], s[52:53]
	s_cbranch_execz .LBB0_1465
	v_ashrrev_i32_e32 v53, 31, v52
	v_lshlrev_b64 v[62:63], 11, v[52:53]
	v_lshl_add_u64 v[62:63], v[74:75], 0, v[62:63]
	global_store_short v[62:63], v58, off

; __device__ __forceinline__ float bf2f(bf16_t v) { return __uint_as_float(((unsigned)v) << 16); }
; __device__ __forceinline__ float sigmoidf_(float x) { return __builtin_amdgcn_rcpf(1.f + __expf(-x)); }
; #define MFMA16(a, b, c) __builtin_amdgcn_mfma_f32_16x16x32_bf16((a), (b), (c), 0, 0, 0)
; __device__ __forceinline__ void rglru_unit(const Params& p, const WS& ws, int j, int u, bool dry = false) {
;     ...
; #pragma unroll
;       for (int ks = 0; ks < 4; ++ks) {
;         const bf16x8 xf = *(const bf16x8*)(XC + (16 * w + lr) * 136 + 32 * ks + 8 * lq);
; #pragma unroll
;         for (int gate = 0; gate < 2; ++gate)
; #pragma unroll
;           for (int mt = 0; mt < 2; ++mt) {
;             const bf16x8 wf = *(const bf16x8*)(WG + (gate * 32 + 16 * mt + lr) * 136 + 32 * ks + 8 * lq);
;             ga_[gate][mt] = MFMA16(wf, xf, ga_[gate][mt]);
;           }
;       }
;       const int tok = 16 * w + lr;
; #pragma unroll
;       for (int mt = 0; mt < 2; ++mt)
; #pragma unroll
;         for (int jj = 0; jj < 4; ++jj) {
;           const int n = 16 * mt + 4 * lq + jj;
;           const float xcv = bf2f(XC[tok * 136 + 32 * jq + n]);
;           const float r = sigmoidf_(ga_[0][mt][jj] + ba[mt][jj]);
;           const float ig = sigmoidf_(ga_[1][mt][jj] + bx[mt][jj]);
;           const float la = -r * sp[mt][jj];
;           const float a = __expf(la);
;           const float x2 = 2.f * la;
;           const float om = x2 > -0.02f ? -x2 * (1.f + 0.5f * x2 * (1.f + x2 * (1.f / 3.f))) : 1.f - a * a;
;           const float mult = __builtin_amdgcn_sqrtf(fmaxf(om, 0.f));
;           AUa[tok * 33 + n] = a;
;           AUu[tok * 33 + n] = mult * ig * xcv;
;         }
.LBB0_1505:
	ds_read_b128 v[52:55], v111
	ds_read_b128 v[56:59], v112 offset:17408
	ds_read_b128 v[60:63], v112 offset:21760
	ds_read_b128 v[64:67], v112 offset:26112
	ds_read_b128 v[120:123], v112 offset:30464
	s_waitcnt lgkmcnt(3)
	v_mfma_f32_16x16x32_bf16 v[56:59], v[56:59], v[52:55], 0
	s_waitcnt lgkmcnt(2)
	v_mfma_f32_16x16x32_bf16 v[60:63], v[60:63], v[52:55], 0
	s_waitcnt lgkmcnt(1)
	v_mfma_f32_16x16x32_bf16 v[64:67], v[64:67], v[52:55], 0
	s_waitcnt lgkmcnt(0)
	v_mfma_f32_16x16x32_bf16 v[52:55], v[120:123], v[52:55], 0
	ds_read_b128 v[120:123], v111 offset:64
	ds_read_b128 v[154:157], v112 offset:17472
	s_waitcnt lgkmcnt(0)
	v_mfma_f32_16x16x32_bf16 v[56:59], v[154:157], v[120:123], v[56:59]
	ds_read_b128 v[154:157], v112 offset:21824
	s_waitcnt lgkmcnt(0)
	v_mfma_f32_16x16x32_bf16 v[60:63], v[154:157], v[120:123], v[60:63]
	ds_read_b128 v[154:157], v112 offset:26176
	s_waitcnt lgkmcnt(0)
	v_mfma_f32_16x16x32_bf16 v[64:67], v[154:157], v[120:123], v[64:67]
	ds_read_b128 v[154:157], v112 offset:30528
	s_waitcnt lgkmcnt(0)
	v_mfma_f32_16x16x32_bf16 v[52:55], v[154:157], v[120:123], v[52:55]
	ds_read_b128 v[120:123], v111 offset:128
	ds_read_b128 v[154:157], v112 offset:17536
	s_waitcnt lgkmcnt(0)
	v_mfma_f32_16x16x32_bf16 v[56:59], v[154:157], v[120:123], v[56:59]
	ds_read_b128 v[154:157], v112 offset:21888
	s_waitcnt lgkmcnt(0)
	v_mfma_f32_16x16x32_bf16 v[60:63], v[154:157], v[120:123], v[60:63]
	ds_read_b128 v[154:157], v112 offset:26240
	s_waitcnt lgkmcnt(0)
	v_mfma_f32_16x16x32_bf16 v[154:157], v[154:157], v[120:123], v[64:67]
	s_nop 2
	ds_read_b128 v[64:67], v112 offset:30592
	s_waitcnt lgkmcnt(0)
	v_mfma_f32_16x16x32_bf16 v[52:55], v[64:67], v[120:123], v[52:55]
	ds_read_b128 v[120:123], v111 offset:192
	ds_read_b128 v[64:67], v112 offset:17600
	ds_read_u16 v15, v113
	s_waitcnt lgkmcnt(1)
	v_mfma_f32_16x16x32_bf16 v[64:67], v[64:67], v[120:123], v[56:59]
	s_nop 2
	ds_read_b128 v[56:59], v112 offset:21952
	s_waitcnt lgkmcnt(0)
	v_mfma_f32_16x16x32_bf16 v[56:59], v[56:59], v[120:123], v[60:63]
	s_nop 2
	ds_read_b128 v[60:63], v112 offset:26304
	v_add_f32_e32 v14, v0, v64
	v_mul_f32_e32 v14, 0xbfb8aa3b, v14
	v_exp_f32_e32 v14, v14
	s_waitcnt lgkmcnt(0)
	v_mfma_f32_16x16x32_bf16 v[60:63], v[60:63], v[120:123], v[154:157]
	s_nop 2
	ds_read_b128 v[154:157], v112 offset:30656
	v_add_f32_e32 v14, 1.0, v14
	v_rcp_f32_e64 v14, -v14
	s_waitcnt lgkmcnt(0)
	v_mfma_f32_16x16x32_bf16 v[52:55], v[154:157], v[120:123], v[52:55]
	v_mul_f32_e32 v14, v89, v14
	v_mul_f32_e32 v64, 0x3fb8aa3b, v14
	v_exp_f32_e32 v64, v64
	v_add_f32_e32 v14, v14, v14
	v_cmp_nlt_f32_e64 s[52:53], s29, v14
	s_and_saveexec_b64 s[4:5], s[52:53]
	s_xor_b64 s[4:5], exec, s[4:5]
	v_fma_f32 v119, -v64, v64, 1.0
	s_andn2_saveexec_b64 s[4:5], s[4:5]
	v_pk_mul_f32 v[120:121], v[14:15], s[88:89] op_sel_hi:[0,1]
	v_add_f32_e32 v119, 1.0, v121
	v_fma_f32 v119, v120, v119, 1.0
	v_mul_f32_e64 v119, v119, -v14
	s_or_b64 exec, exec, s[4:5]
	v_add_f32_e32 v14, v8, v60
	v_add_f32_e32 v65, v1, v65
	v_mul_f32_e32 v14, 0xbfb8aa3b, v14
	v_mul_f32_e32 v65, 0xbfb8aa3b, v65
	v_exp_f32_e32 v14, v14
	v_exp_f32_e32 v65, v65
	v_max_f32_e32 v60, v119, v119
	v_max_f32_e32 v60, 0, v60
	v_add_f32_e32 v14, 1.0, v14
	v_add_f32_e32 v65, 1.0, v65
	v_rcp_f32_e32 v14, v14
	v_sqrt_f32_e32 v60, v60
	v_rcp_f32_e64 v65, -v65
	v_lshlrev_b32_e32 v15, 16, v15
	v_mul_f32_e32 v14, v14, v60
	v_mul_f32_e32 v65, v93, v65
	v_mul_f32_e32 v14, v14, v15
	ds_read_u16 v60, v113 offset:2
	v_mul_f32_e32 v15, 0x3fb8aa3b, v65
	v_exp_f32_e32 v15, v15
	ds_write2st64_b32 v72, v64, v14 offset0:136 offset1:169
	v_add_f32_e32 v14, v65, v65
	v_cmp_nlt_f32_e64 s[52:53], s29, v14
	s_and_saveexec_b64 s[4:5], s[52:53]
	s_xor_b64 s[4:5], exec, s[4:5]
	v_fma_f32 v64, -v15, v15, 1.0
	s_andn2_saveexec_b64 s[4:5], s[4:5]
	v_pk_mul_f32 v[64:65], v[14:15], s[88:89] op_sel_hi:[0,1]
	v_add_f32_e32 v65, 1.0, v65
	v_fma_f32 v64, v64, v65, 1.0
	v_mul_f32_e64 v64, v64, -v14
	s_or_b64 exec, exec, s[4:5]
	v_add_f32_e32 v14, v9, v61
	v_max_f32_e32 v61, v64, v64
	v_add_f32_e32 v64, v2, v66
	v_mul_f32_e32 v14, 0xbfb8aa3b, v14
	v_mul_f32_e32 v64, 0xbfb8aa3b, v64
	v_exp_f32_e32 v14, v14
	v_exp_f32_e32 v64, v64
	v_max_f32_e32 v61, 0, v61
	v_sqrt_f32_e32 v61, v61
	v_add_f32_e32 v14, 1.0, v14
	v_add_f32_e32 v64, 1.0, v64
	v_rcp_f32_e32 v14, v14
	v_rcp_f32_e64 v64, -v64
	s_waitcnt lgkmcnt(1)
	v_lshlrev_b32_e32 v60, 16, v60
	v_mul_f32_e32 v14, v14, v61
	v_mul_f32_e32 v64, v95, v64
	v_mul_f32_e32 v14, v14, v60
	ds_read_u16 v61, v113 offset:4
	v_mul_f32_e32 v60, 0x3fb8aa3b, v64
	v_exp_f32_e32 v60, v60
	ds_write2st64_b32 v135, v15, v14 offset0:136 offset1:169
	v_add_f32_e32 v14, v64, v64
	v_cmp_nlt_f32_e64 s[52:53], s29, v14
	s_and_saveexec_b64 s[4:5], s[52:53]
	s_xor_b64 s[4:5], exec, s[4:5]
	v_fma_f32 v15, -v60, v60, 1.0
	s_andn2_saveexec_b64 s[4:5], s[4:5]
	v_pk_mul_f32 v[64:65], v[14:15], s[88:89] op_sel_hi:[0,1]
	v_add_f32_e32 v15, 1.0, v65
	v_fma_f32 v15, v64, v15, 1.0
	v_mul_f32_e64 v15, v15, -v14
	s_or_b64 exec, exec, s[4:5]
	v_add_f32_e32 v14, v10, v62
	v_add_f32_e32 v62, v3, v67
	v_mul_f32_e32 v14, 0xbfb8aa3b, v14
	v_mul_f32_e32 v62, 0xbfb8aa3b, v62
	v_exp_f32_e32 v14, v14
	v_exp_f32_e32 v62, v62
	v_max_f32_e32 v15, v15, v15
	v_max_f32_e32 v15, 0, v15
	v_add_f32_e32 v14, 1.0, v14
	v_add_f32_e32 v62, 1.0, v62
	v_rcp_f32_e32 v14, v14
	v_sqrt_f32_e32 v15, v15
	v_rcp_f32_e64 v62, -v62
	s_waitcnt lgkmcnt(1)
; __device__ __forceinline__ float bf2f(bf16_t v) { return __uint_as_float(((unsigned)v) << 16); }
; __device__ __forceinline__ float sigmoidf_(float x) { return __builtin_amdgcn_rcpf(1.f + __expf(-x)); }
; __device__ __forceinline__ void rglru_unit(const Params& p, const WS& ws, int j, int u, bool dry = false) {
;     ...
; #pragma unroll
;       for (int mt = 0; mt < 2; ++mt)
; #pragma unroll
;         for (int jj = 0; jj < 4; ++jj) {
;           const int n = 16 * mt + 4 * lq + jj;
;           const float xcv = bf2f(XC[tok * 136 + 32 * jq + n]);
;           const float r = sigmoidf_(ga_[0][mt][jj] + ba[mt][jj]);
;           const float ig = sigmoidf_(ga_[1][mt][jj] + bx[mt][jj]);
;           const float la = -r * sp[mt][jj];
;           const float a = __expf(la);
;           const float x2 = 2.f * la;
;           const float om = x2 > -0.02f ? -x2 * (1.f + 0.5f * x2 * (1.f + x2 * (1.f / 3.f))) : 1.f - a * a;
;           const float mult = __builtin_amdgcn_sqrtf(fmaxf(om, 0.f));
;           AUa[tok * 33 + n] = a;
;           AUu[tok * 33 + n] = mult * ig * xcv;
;         }
;     }
;     __syncthreads();
;     {
;       float A = 1.f, Hh = 0.f;
; #pragma unroll
;       for (int i = 0; i < 8; ++i) {
;         const float a = AUa[(8 * ssg + i) * 33 + sc], uu = AUu[(8 * ssg + i) * 33 + sc];
;         Hh = a * Hh + uu; A *= a;
;       }
;       SEGA[ssg * 32 + sc] = A; SEGH[ssg * 32 + sc] = Hh;
;     }
;     __syncthreads();
;     float hin = CARRY[sc];
; #pragma unroll
;     for (int s2 = 0; s2 < 7; ++s2)
;       if (s2 < ssg) hin = SEGA[s2 * 32 + sc] * hin + SEGH[s2 * 32 + sc];
	v_lshlrev_b32_e32 v61, 16, v61
	v_mul_f32_e32 v14, v14, v15
	v_mul_f32_e32 v62, v96, v62
	v_mul_f32_e32 v14, v14, v61
	ds_read_u16 v61, v113 offset:6
	v_mul_f32_e32 v15, 0x3fb8aa3b, v62
	v_exp_f32_e32 v15, v15
	ds_write2st64_b32 v136, v60, v14 offset0:136 offset1:169
	v_add_f32_e32 v14, v62, v62
	v_cmp_nlt_f32_e64 s[52:53], s29, v14
	s_and_saveexec_b64 s[4:5], s[52:53]
	s_xor_b64 s[4:5], exec, s[4:5]
	v_fma_f32 v60, -v15, v15, 1.0
	s_andn2_saveexec_b64 s[4:5], s[4:5]
	v_pk_mul_f32 v[64:65], v[14:15], s[88:89] op_sel_hi:[0,1]
	v_add_f32_e32 v60, 1.0, v65
	v_fma_f32 v60, v64, v60, 1.0
	v_mul_f32_e64 v60, v60, -v14
	s_or_b64 exec, exec, s[4:5]
	v_add_f32_e32 v14, v11, v63
	v_mul_f32_e32 v14, 0xbfb8aa3b, v14
	v_add_f32_e32 v56, v4, v56
	v_exp_f32_e32 v14, v14
	v_mul_f32_e32 v56, 0xbfb8aa3b, v56
	v_exp_f32_e32 v56, v56
	v_max_f32_e32 v60, v60, v60
	v_add_f32_e32 v14, 1.0, v14
	v_max_f32_e32 v60, 0, v60
	v_rcp_f32_e32 v14, v14
	v_sqrt_f32_e32 v60, v60
	v_add_f32_e32 v56, 1.0, v56
	v_rcp_f32_e64 v56, -v56
	s_waitcnt lgkmcnt(1)
	v_lshlrev_b32_e32 v61, 16, v61
	v_mul_f32_e32 v14, v14, v60
	v_mul_f32_e32 v14, v14, v61
	v_mul_f32_e32 v61, v97, v56
	ds_read_u16 v60, v113 offset:32
	v_mul_f32_e32 v56, 0x3fb8aa3b, v61
	v_exp_f32_e32 v56, v56
	ds_write2st64_b32 v139, v15, v14 offset0:136 offset1:169
	v_add_f32_e32 v14, v61, v61
	v_cmp_nlt_f32_e64 s[52:53], s29, v14
	s_and_saveexec_b64 s[4:5], s[52:53]
	s_xor_b64 s[4:5], exec, s[4:5]
	v_fma_f32 v15, -v56, v56, 1.0
	s_andn2_saveexec_b64 s[4:5], s[4:5]
	v_pk_mul_f32 v[62:63], v[14:15], s[88:89] op_sel_hi:[0,1]
	v_add_f32_e32 v15, 1.0, v63
	v_fma_f32 v15, v62, v15, 1.0
	v_mul_f32_e64 v15, v15, -v14
	s_or_b64 exec, exec, s[4:5]
	v_add_f32_e32 v14, v16, v52
	v_mul_f32_e32 v14, 0xbfb8aa3b, v14
	v_add_f32_e32 v52, v5, v57
	v_exp_f32_e32 v14, v14
	v_mul_f32_e32 v52, 0xbfb8aa3b, v52
	v_exp_f32_e32 v52, v52
	v_max_f32_e32 v15, v15, v15
	v_add_f32_e32 v14, 1.0, v14
	v_max_f32_e32 v15, 0, v15
	v_rcp_f32_e32 v14, v14
	v_sqrt_f32_e32 v15, v15
	v_add_f32_e32 v52, 1.0, v52
	s_waitcnt lgkmcnt(1)
	v_lshlrev_b32_e32 v57, 16, v60
	v_rcp_f32_e64 v60, -v52
	v_mul_f32_e32 v14, v14, v15
	v_mul_f32_e32 v14, v14, v57
	ds_read_u16 v52, v113 offset:34
	v_mul_f32_e32 v57, v98, v60
	v_mul_f32_e32 v15, 0x3fb8aa3b, v57
	v_exp_f32_e32 v15, v15
	ds_write2st64_b32 v141, v56, v14 offset0:136 offset1:169
	v_add_f32_e32 v14, v57, v57
	v_cmp_nlt_f32_e64 s[52:53], s29, v14
	s_and_saveexec_b64 s[4:5], s[52:53]
	s_xor_b64 s[4:5], exec, s[4:5]
	v_fma_f32 v56, -v15, v15, 1.0
	s_andn2_saveexec_b64 s[4:5], s[4:5]
	v_pk_mul_f32 v[56:57], v[14:15], s[88:89] op_sel_hi:[0,1]
	v_add_f32_e32 v57, 1.0, v57
	v_fma_f32 v56, v56, v57, 1.0
	v_mul_f32_e64 v56, v56, -v14
	s_or_b64 exec, exec, s[4:5]
	v_add_f32_e32 v14, v17, v53
	v_max_f32_e32 v53, v56, v56
	v_add_f32_e32 v56, v6, v58
	v_mul_f32_e32 v14, 0xbfb8aa3b, v14
	v_mul_f32_e32 v56, 0xbfb8aa3b, v56
	v_exp_f32_e32 v14, v14
	v_exp_f32_e32 v56, v56
	v_max_f32_e32 v53, 0, v53
	v_sqrt_f32_e32 v53, v53
	v_add_f32_e32 v14, 1.0, v14
	v_add_f32_e32 v56, 1.0, v56
	v_rcp_f32_e32 v14, v14
	v_rcp_f32_e64 v56, -v56
	s_waitcnt lgkmcnt(1)
	v_lshlrev_b32_e32 v52, 16, v52
	v_mul_f32_e32 v14, v14, v53
	v_mul_f32_e32 v56, v99, v56
	v_mul_f32_e32 v14, v14, v52
	ds_read_u16 v53, v113 offset:36
	v_mul_f32_e32 v52, 0x3fb8aa3b, v56
	v_exp_f32_e32 v52, v52
	ds_write2st64_b32 v142, v15, v14 offset0:136 offset1:169
	v_add_f32_e32 v14, v56, v56
	v_cmp_nlt_f32_e64 s[52:53], s29, v14
	s_and_saveexec_b64 s[4:5], s[52:53]
	s_xor_b64 s[4:5], exec, s[4:5]
	v_fma_f32 v15, -v52, v52, 1.0
	s_andn2_saveexec_b64 s[4:5], s[4:5]
	v_pk_mul_f32 v[56:57], v[14:15], s[88:89] op_sel_hi:[0,1]
	v_add_f32_e32 v15, 1.0, v57
	v_fma_f32 v15, v56, v15, 1.0
	v_mul_f32_e64 v15, v15, -v14
	s_or_b64 exec, exec, s[4:5]
	v_add_f32_e32 v14, v18, v54
	v_add_f32_e32 v54, v7, v59
	v_mul_f32_e32 v14, 0xbfb8aa3b, v14
	v_mul_f32_e32 v54, 0xbfb8aa3b, v54
	v_exp_f32_e32 v14, v14
	v_exp_f32_e32 v54, v54
	v_max_f32_e32 v15, v15, v15
	v_max_f32_e32 v15, 0, v15
	v_add_f32_e32 v14, 1.0, v14
	v_add_f32_e32 v54, 1.0, v54
	v_rcp_f32_e32 v14, v14
	v_sqrt_f32_e32 v15, v15
	v_rcp_f32_e64 v54, -v54
	s_waitcnt lgkmcnt(1)
	v_lshlrev_b32_e32 v53, 16, v53
	v_mul_f32_e32 v14, v14, v15
	v_mul_f32_e32 v54, v105, v54
	v_mul_f32_e32 v14, v14, v53
	ds_read_u16 v53, v113 offset:38
	v_mul_f32_e32 v15, 0x3fb8aa3b, v54
	v_exp_f32_e32 v15, v15
	ds_write2st64_b32 v144, v52, v14 offset0:136 offset1:169
	v_add_f32_e32 v14, v54, v54
	v_cmp_nlt_f32_e64 s[52:53], s29, v14
	s_and_saveexec_b64 s[4:5], s[52:53]
	s_xor_b64 s[4:5], exec, s[4:5]
	v_fma_f32 v52, -v15, v15, 1.0
	s_andn2_saveexec_b64 s[4:5], s[4:5]
	v_pk_mul_f32 v[56:57], v[14:15], s[88:89] op_sel_hi:[0,1]
	v_add_f32_e32 v52, 1.0, v57
	v_fma_f32 v52, v56, v52, 1.0
	v_mul_f32_e64 v52, v52, -v14
	s_or_b64 exec, exec, s[4:5]
	s_waitcnt lgkmcnt(1)
	v_lshlrev_b32_e32 v14, 16, v53
	v_add_f32_e32 v53, v19, v55
	v_mul_f32_e32 v53, 0xbfb8aa3b, v53
	v_exp_f32_e32 v53, v53
	v_max_f32_e32 v52, v52, v52
	v_max_f32_e32 v52, 0, v52
	v_sqrt_f32_e32 v52, v52
	v_add_f32_e32 v53, 1.0, v53
	v_rcp_f32_e32 v53, v53
	s_nop 0
	v_mul_f32_e32 v52, v53, v52
	v_mul_f32_e32 v14, v52, v14
	ds_write2st64_b32 v145, v15, v14 offset0:136 offset1:169
	s_waitcnt lgkmcnt(0)
	s_barrier
	ds_read2_b32 v[242:243], v137 offset1:33
	ds_read2_b32 v[244:245], v138 offset0:64 offset1:97
	ds_read2_b32 v[246:247], v137 offset0:66 offset1:99
	ds_read2_b32 v[248:249], v138 offset0:130 offset1:163
	ds_read2_b32 v[250:251], v137 offset0:132 offset1:165
	ds_read2_b32 v[252:253], v138 offset0:196 offset1:229
	ds_read2_b32 v[14:15], v137 offset0:198 offset1:231
	ds_read2_b32 v[54:55], v140 offset0:6 offset1:39
	s_waitcnt lgkmcnt(6)
	v_fma_f32 v244, 0, v242, v244
	v_fmac_f32_e32 v245, v244, v243
	v_mul_f32_e32 v255, v242, v243
	s_waitcnt lgkmcnt(4)
	v_fma_f32 v245, v245, v246, v248
	v_mul_f32_e32 v246, v255, v246
	v_fmac_f32_e32 v249, v245, v247
	v_mul_f32_e32 v254, v246, v247
	s_waitcnt lgkmcnt(2)
	v_fma_f32 v252, v249, v250, v252
	v_mul_f32_e32 v250, v254, v250
	v_fmac_f32_e32 v253, v252, v251
	v_mul_f32_e32 v52, v250, v251
	s_waitcnt lgkmcnt(0)
	v_fma_f32 v253, v253, v14, v54
	v_mul_f32_e32 v14, v52, v14
	v_fmac_f32_e32 v55, v253, v15
	v_mul_f32_e32 v14, v14, v15
	ds_write2st64_b32 v78, v14, v55 offset0:202 offset1:206
	s_waitcnt lgkmcnt(0)
	s_barrier
	ds_read_b32 v14, v115 offset:53760
	s_and_saveexec_b64 s[4:5], vcc
	s_cbranch_execz .LBB0_1557
	ds_read2st64_b32 v[52:53], v115 offset0:202 offset1:206
	s_waitcnt lgkmcnt(0)
	v_fmac_f32_e32 v53, v14, v52
	v_mov_b32_e32 v14, v53
	s_or_b64 exec, exec, s[4:5]
	s_and_saveexec_b64 s[4:5], s[38:39]
	s_cbranch_execnz .LBB0_1558

; __device__ __forceinline__ bf16_t f2bf(float f) { return (bf16_t)(cvt_pk_bf16(f, 0.f) & 0xffffu); }
; __device__ __forceinline__ float siluf_(float x) { return x * __builtin_amdgcn_rcpf(1.f + __expf(-x)); }
; __device__ __forceinline__ void rglru_unit(const Params& p, const WS& ws, int j, int u, bool dry = false) {
;     ...
;     {
;       float h = hin;
; #pragma unroll
;       for (int i = 0; i < 8; ++i) {
;         const float a = AUa[(8 * ssg + i) * 33 + sc], uu = AUu[(8 * ssg + i) * 33 + sc];
;         h = a * h + uu;
;         const int t = t0 + 8 * ssg + i;
;         ypend[i] = f2bf(h * siluf_(gcur[i]));
;       }
;       if (ssg == 7) CARRY[sc] = h;
;       ypend_t0 = t0;
.LBB0_1545:
	s_or_b64 exec, exec, s[4:5]
	s_waitcnt lgkmcnt(0)
	s_barrier
	v_mov_b32_e32 v255, v14
	ds_read2_b32 v[242:243], v137 offset1:33
	ds_read2_b32 v[56:57], v138 offset0:64 offset1:97
	ds_read2_b32 v[244:245], v137 offset0:66 offset1:99
	ds_read2_b32 v[54:55], v138 offset0:130 offset1:163
	ds_read2_b32 v[246:247], v137 offset0:132 offset1:165
	ds_read2_b32 v[52:53], v138 offset0:196 offset1:229
	ds_read2_b32 v[58:59], v137 offset0:198 offset1:231
	ds_read2_b32 v[14:15], v140 offset0:6 offset1:39
	s_waitcnt lgkmcnt(6)
	v_fma_f32 v56, v255, v242, v56
	v_fmac_f32_e32 v57, v56, v243
	s_waitcnt lgkmcnt(4)
	v_fma_f32 v54, v57, v244, v54
	v_fmac_f32_e32 v55, v54, v245
	s_waitcnt lgkmcnt(2)
	v_fma_f32 v52, v55, v246, v52
	v_fmac_f32_e32 v53, v52, v247
	s_waitcnt lgkmcnt(0)
	v_fma_f32 v14, v53, v58, v14
	v_fmac_f32_e32 v15, v14, v59
	s_and_saveexec_b64 s[4:5], s[50:51]
	ds_write_b32 v115, v15 offset:53760
	s_or_b64 exec, exec, s[4:5]
	v_lshlrev_b32_e32 v58, 16, v86
	v_mul_f32_e32 v66, 0xbfb8aa3b, v58
	v_exp_f32_e32 v66, v66
	v_lshlrev_b32_e32 v59, 16, v85
	v_lshlrev_b32_e32 v60, 16, v88
	v_lshlrev_b32_e32 v61, 16, v87
	v_add_f32_e32 v66, 1.0, v66
	v_rcp_f32_e32 v66, v66
	v_lshlrev_b32_e32 v62, 16, v91
	v_lshlrev_b32_e32 v63, 16, v90
	v_lshlrev_b32_e32 v64, 16, v92
	v_mul_f32_e32 v58, v66, v58
	v_mul_f32_e32 v56, v58, v56
	v_cvt_pk_bf16_f32 v58, v56, s0
	v_mul_f32_e32 v56, 0xbfb8aa3b, v59
	v_exp_f32_e32 v56, v56
	v_lshlrev_b32_e32 v65, 16, v94
	s_add_i32 s4, s6, 64
	v_add_f32_e32 v56, 1.0, v56
	v_rcp_f32_e32 v56, v56
	s_nop 0
	v_mul_f32_e32 v56, v56, v59
	v_mul_f32_e32 v56, v56, v57
	v_cvt_pk_bf16_f32 v59, v56, s0
	v_mul_f32_e32 v56, 0xbfb8aa3b, v60
	v_exp_f32_e32 v56, v56
	s_nop 0
	v_add_f32_e32 v56, 1.0, v56
	v_rcp_f32_e32 v56, v56
	s_nop 0
	v_mul_f32_e32 v56, v56, v60
	v_mul_f32_e32 v54, v56, v54
	v_cvt_pk_bf16_f32 v56, v54, s0
	v_mul_f32_e32 v54, 0xbfb8aa3b, v61
	v_exp_f32_e32 v54, v54
	s_nop 0
	v_add_f32_e32 v54, 1.0, v54
	v_rcp_f32_e32 v54, v54
	s_nop 0
	v_mul_f32_e32 v54, v54, v61
	v_mul_f32_e32 v54, v54, v55
	v_cvt_pk_bf16_f32 v57, v54, s0
	v_mul_f32_e32 v54, 0xbfb8aa3b, v62
	v_exp_f32_e32 v54, v54
	s_nop 0
	v_add_f32_e32 v54, 1.0, v54
	v_rcp_f32_e32 v54, v54
	s_nop 0
	v_mul_f32_e32 v54, v54, v62
	v_mul_f32_e32 v52, v54, v52
	v_cvt_pk_bf16_f32 v54, v52, s0
	v_mul_f32_e32 v52, 0xbfb8aa3b, v63
	v_exp_f32_e32 v52, v52
	s_nop 0
	v_add_f32_e32 v52, 1.0, v52
	v_rcp_f32_e32 v52, v52
	s_nop 0
	v_mul_f32_e32 v52, v52, v63
	v_mul_f32_e32 v52, v52, v53
	v_cvt_pk_bf16_f32 v55, v52, s0
	v_mul_f32_e32 v52, 0xbfb8aa3b, v64
	v_exp_f32_e32 v52, v52
	s_nop 0
	v_add_f32_e32 v52, 1.0, v52
	v_rcp_f32_e32 v52, v52
	s_nop 0
	v_mul_f32_e32 v52, v52, v64
	v_mul_f32_e32 v14, v52, v14
	v_mul_f32_e32 v52, 0xbfb8aa3b, v65
	v_exp_f32_e32 v52, v52
	v_cvt_pk_bf16_f32 v14, v14, s0
	v_add_f32_e32 v52, 1.0, v52
	v_rcp_f32_e32 v52, v52
	s_nop 0
	v_mul_f32_e32 v52, v52, v65
	v_mul_f32_e32 v15, v52, v15
	v_cvt_pk_bf16_f32 v15, v15, s0
	s_branch .LBB0_1555
